# attention key loop: (t2=0,s2=1) PV operands packed before the second exp block into spare quads, its four MFMAs interleaved into the exp block
# speedup vs baseline: 1.0037x; 1.0026x over previous
; #define SB_ __builtin_amdgcn_sched_barrier(0)
; DI void attn_item64(const Params& p, int it, char* smem) {
;     ...
;   for (int kt = 0; kt < NKT; ++kt) {
;     const char* cur = smem + (kt & 1) * STAGE;
;     const bool more = kt + 1 < NKT;
;     if (more) {
;       const bf16_t* kn = Kb + (size_t)(kt + 1) * 64 * QKD; const bf16_t* vn = Vb + (kt + 1) * 64;
;       char* nx = smem + ((kt + 1) & 1) * STAGE;
;       GLDS(kn + kgo0, nx + klo0); if (k1v) GLDS(kn + kgo1, nx + klo1);
;       rv0 = *(const uint4*)(vn + vgo0);
;     }
;     SB_;
; #pragma unroll
;     for (int t2 = 0; t2 < 2; ++t2) {
;       const char* kpe = cur + (t2 * 32 + r) * KROW + swo;
;       const char* kpo = kpe - 2 * sb32;
;       f32x16 sa, sb;
;       { const bf16x8 kf = *(const bf16x8*)(kpe); sa = MFMA(kf, qfa[0], sinit); sb = MFMA(kf, qfb[0], sinit); }
; #pragma unroll
;       for (int c = 1; c < 6; ++c) { const bf16x8 kf = *(const bf16x8*)(((c & 1) ? kpo : kpe) + c * 32); sa = MFMA(kf, qfa[c], sa); sb = MFMA(kf, qfb[c], sb); }
;       SB_;
;       float lsa = 0.f, lsb = 0.f;
; #pragma unroll
;       for (int i = 0; i < 16; ++i) { const float e = __builtin_amdgcn_exp2f(sa[i]); sa[i] = e; lsa += e; const float f = __builtin_amdgcn_exp2f(sb[i]); sb[i] = f; lsb += f; }
;       la += lsa; lb += lsb;
;       SB_;
; #pragma unroll
;       for (int s2 = 0; s2 < 2; ++s2) {
;         uint4 pu, pv;
;         pu.x = pk_bf16(sa[8 * s2 + 0], sa[8 * s2 + 1]); pu.y = pk_bf16(sa[8 * s2 + 2], sa[8 * s2 + 3]); pu.z = pk_bf16(sa[8 * s2 + 4], sa[8 * s2 + 5]); pu.w = pk_bf16(sa[8 * s2 + 6], sa[8 * s2 + 7]);
;         pv.x = pk_bf16(sb[8 * s2 + 0], sb[8 * s2 + 1]); pv.y = pk_bf16(sb[8 * s2 + 2], sb[8 * s2 + 3]); pv.z = pk_bf16(sb[8 * s2 + 4], sb[8 * s2 + 5]); pv.w = pk_bf16(sb[8 * s2 + 6], sb[8 * s2 + 7]);
;         const bf16x8 pa_ = __builtin_bit_cast(bf16x8, pu), pb_ = __builtin_bit_cast(bf16x8, pv);
; #pragma unroll
;         for (int vt = 0; vt < 2; ++vt) {
;           const char* vp = cur + KBYTES + (vt * 32 + r) * VROW + (t2 * 32 + 16 * s2 + 4 * hh) * 2;
;           const uint2 lo = *(const uint2*)(vp), hi = *(const uint2*)(vp + 16);
;           uint4 vu; vu.x = lo.x; vu.y = lo.y; vu.z = hi.x; vu.w = hi.y;
;           const bf16x8 vf = __builtin_bit_cast(bf16x8, vu);
;           oa[vt] = MFMA(vf, pa_, oa[vt]);
;           ob[vt] = MFMA(vf, pb_, ob[vt]);
;         }
;       }
.LBB0_548:
	s_or_b64 exec, exec, s[4:5]
	global_load_dwordx4 v[160:163], v[170:171], off
	s_cmp_eq_u32 s7, 1
	s_cselect_b32 s4, 0, 0x5200
	v_or_b32_e32 v80, s4, v211
	v_add_u32_e32 v80, v80, v210
	v_or_b32_e32 v81, s4, v164
	v_add_u32_e32 v168, v80, v212
	v_add3_u32 v213, v80, v207, v206
	v_add_u32_e32 v80, s6, v209
	v_add_u32_e32 v188, v168, v206
	v_add_u32_e32 v195, v81, v208
	v_add_u32_e32 v238, 0x3000, v80
	ds_read_b128 v[176:179], v168
	ds_read_b128 v[242:245], v188 offset:32
	ds_read_b128 v[180:183], v168 offset:64
	ds_read_b128 v[246:249], v188 offset:96
	ds_read_b128 v[184:187], v168 offset:128
	s_waitcnt lgkmcnt(4)
	v_mfma_f32_32x32x16_bf16 v[80:95], v[176:179], v[152:155], v[64:79]
	v_mfma_f32_32x32x16_bf16 v[96:111], v[176:179], v[156:159], v[64:79]
	ds_read_b128 v[176:179], v188 offset:160
	s_waitcnt lgkmcnt(4)
	v_mfma_f32_32x32x16_bf16 v[80:95], v[242:245], v[136:139], v[80:95]
	v_mfma_f32_32x32x16_bf16 v[96:111], v[242:245], v[140:143], v[96:111]
	s_waitcnt lgkmcnt(3)
	v_mfma_f32_32x32x16_bf16 v[80:95], v[180:183], v[144:147], v[80:95]
	v_mfma_f32_32x32x16_bf16 v[96:111], v[180:183], v[148:151], v[96:111]
	s_waitcnt lgkmcnt(2)
	v_mfma_f32_32x32x16_bf16 v[80:95], v[246:249], v[112:115], v[80:95]
	v_mfma_f32_32x32x16_bf16 v[96:111], v[246:249], v[124:127], v[96:111]
	s_waitcnt lgkmcnt(1)
	v_mfma_f32_32x32x16_bf16 v[80:95], v[184:187], v[128:131], v[80:95]
	v_mfma_f32_32x32x16_bf16 v[96:111], v[184:187], v[132:135], v[96:111]
	s_waitcnt lgkmcnt(0)
	v_mfma_f32_32x32x16_bf16 v[80:95], v[176:179], v[116:119], v[80:95]
	v_mfma_f32_32x32x16_bf16 v[96:111], v[176:179], v[120:123], v[96:111]
	v_add_u32_e32 v239, 0x3000, v195
	v_add_u32_e32 v240, 0x4000, v195
	ds_read2_b64 v[242:245], v239 offset1:2
	ds_read2_b64 v[246:249], v240 offset0:32 offset1:34
	s_nop 10
	v_exp_f32_e32 v214, v80
	v_exp_f32_e32 v215, v81
	v_exp_f32_e32 v216, v82
	v_exp_f32_e32 v217, v83
	v_add_f32_e32 v80, 0, v214
	v_exp_f32_e32 v218, v84
	v_add_f32_e32 v80, v215, v80
	v_exp_f32_e32 v219, v85
	v_add_f32_e32 v80, v216, v80
	v_exp_f32_e32 v222, v86
	v_add_f32_e32 v80, v217, v80
	v_add_f32_e32 v80, v218, v80
	v_add_f32_e32 v80, v219, v80
	v_exp_f32_e32 v96, v96
	v_exp_f32_e32 v97, v97
	v_exp_f32_e32 v98, v98
	v_exp_f32_e32 v99, v99
	v_exp_f32_e32 v100, v100
	v_exp_f32_e32 v101, v101
	v_exp_f32_e32 v102, v102
	v_exp_f32_e32 v188, v87
	v_exp_f32_e32 v189, v103
	v_exp_f32_e32 v186, v88
	v_exp_f32_e32 v187, v104
	v_exp_f32_e32 v190, v89
	v_exp_f32_e32 v191, v105
	v_exp_f32_e32 v192, v90
	v_exp_f32_e32 v193, v106
	v_exp_f32_e32 v180, v91
	v_exp_f32_e32 v181, v107
	v_exp_f32_e32 v182, v92
	v_exp_f32_e32 v183, v108
	v_exp_f32_e32 v184, v93
	v_exp_f32_e32 v185, v109
	v_exp_f32_e32 v176, v94
	v_exp_f32_e32 v177, v110
	v_exp_f32_e32 v178, v95
	v_exp_f32_e32 v179, v111
	v_add_f32_e32 v194, v222, v80
	v_cvt_pk_bf16_f32 v84, v214, v215
	v_cvt_pk_bf16_f32 v85, v216, v217
	v_cvt_pk_bf16_f32 v86, v218, v219
	v_cvt_pk_bf16_f32 v87, v222, v188
	v_cvt_pk_bf16_f32 v88, v96, v97
	v_cvt_pk_bf16_f32 v89, v98, v99
	v_cvt_pk_bf16_f32 v90, v100, v101
	v_cvt_pk_bf16_f32 v91, v102, v189
	s_waitcnt lgkmcnt(0)
	v_mfma_f32_32x32x16_bf16 v[48:63], v[242:245], v[84:87], v[48:63]
	v_mfma_f32_32x32x16_bf16 v[32:47], v[242:245], v[88:91], v[32:47]
	ds_read2_b64 v[214:217], v239 offset0:4 offset1:6
	ds_read2_b64 v[222:225], v240 offset0:36 offset1:38
	s_waitcnt lgkmcnt(2)
	v_mfma_f32_32x32x16_bf16 v[16:31], v[246:249], v[84:87], v[16:31]
	v_add_f32_e32 v84, 0, v96
	v_add_f32_e32 v84, v97, v84
	v_add_f32_e32 v84, v98, v84
	v_add_f32_e32 v84, v99, v84
	v_add_f32_e32 v84, v100, v84
	v_add_f32_e32 v84, v101, v84
	v_add_f32_e32 v195, v102, v84
	v_mfma_f32_32x32x16_bf16 v[0:15], v[246:249], v[88:91], v[0:15]
	ds_read_b128 v[226:229], v168 offset:6144
	ds_read_b128 v[242:245], v213 offset:32
	ds_read_b128 v[230:233], v168 offset:6208
	ds_read_b128 v[246:249], v213 offset:96
	ds_read_b128 v[234:237], v168 offset:6272
	s_waitcnt lgkmcnt(4)
	v_mfma_f32_32x32x16_bf16 v[80:95], v[226:229], v[152:155], v[64:79]
	v_mfma_f32_32x32x16_bf16 v[96:111], v[226:229], v[156:159], v[64:79]
	ds_read_b128 v[226:229], v213 offset:160
	s_waitcnt lgkmcnt(4)
	v_mfma_f32_32x32x16_bf16 v[80:95], v[242:245], v[136:139], v[80:95]
	v_mfma_f32_32x32x16_bf16 v[96:111], v[242:245], v[140:143], v[96:111]
	s_waitcnt lgkmcnt(3)
	v_mfma_f32_32x32x16_bf16 v[80:95], v[230:233], v[144:147], v[80:95]
	v_mfma_f32_32x32x16_bf16 v[96:111], v[230:233], v[148:151], v[96:111]
	s_waitcnt lgkmcnt(2)
	v_mfma_f32_32x32x16_bf16 v[80:95], v[246:249], v[112:115], v[80:95]
	v_mfma_f32_32x32x16_bf16 v[96:111], v[246:249], v[124:127], v[96:111]
	s_waitcnt lgkmcnt(1)
	v_mfma_f32_32x32x16_bf16 v[80:95], v[234:237], v[128:131], v[80:95]
	v_mfma_f32_32x32x16_bf16 v[96:111], v[234:237], v[132:135], v[96:111]
	s_waitcnt lgkmcnt(0)
; #define MFMA(a, b, c) __builtin_amdgcn_mfma_f32_32x32x16_bf16((a), (b), (c), 0, 0, 0)
; DI unsigned pk_bf16(float lo, float hi) { f32x2v v = {lo, hi}; bf16x2v b = __builtin_convertvector(v, bf16x2v); return __builtin_bit_cast(unsigned, b); }
; #define SB_ __builtin_amdgcn_sched_barrier(0)
; DI void attn_item64(const Params& p, int it, char* smem) {
;     ...
;     for (int t2 = 0; t2 < 2; ++t2) {
;       const char* kpe = cur + (t2 * 32 + r) * KROW + swo;
;       const char* kpo = kpe - 2 * sb32;
;       f32x16 sa, sb;
;       { const bf16x8 kf = *(const bf16x8*)(kpe); sa = MFMA(kf, qfa[0], sinit); sb = MFMA(kf, qfb[0], sinit); }
; #pragma unroll
;       for (int c = 1; c < 6; ++c) { const bf16x8 kf = *(const bf16x8*)(((c & 1) ? kpo : kpe) + c * 32); sa = MFMA(kf, qfa[c], sa); sb = MFMA(kf, qfb[c], sb); }
;       SB_;
;       float lsa = 0.f, lsb = 0.f;
; #pragma unroll
;       for (int i = 0; i < 16; ++i) { const float e = __builtin_amdgcn_exp2f(sa[i]); sa[i] = e; lsa += e; const float f = __builtin_amdgcn_exp2f(sb[i]); sb[i] = f; lsb += f; }
;       la += lsa; lb += lsb;
;       SB_;
; #pragma unroll
;       for (int s2 = 0; s2 < 2; ++s2) {
;         uint4 pu, pv;
;         pu.x = pk_bf16(sa[8 * s2 + 0], sa[8 * s2 + 1]); pu.y = pk_bf16(sa[8 * s2 + 2], sa[8 * s2 + 3]); pu.z = pk_bf16(sa[8 * s2 + 4], sa[8 * s2 + 5]); pu.w = pk_bf16(sa[8 * s2 + 6], sa[8 * s2 + 7]);
;         pv.x = pk_bf16(sb[8 * s2 + 0], sb[8 * s2 + 1]); pv.y = pk_bf16(sb[8 * s2 + 2], sb[8 * s2 + 3]); pv.z = pk_bf16(sb[8 * s2 + 4], sb[8 * s2 + 5]); pv.w = pk_bf16(sb[8 * s2 + 6], sb[8 * s2 + 7]);
;         const bf16x8 pa_ = __builtin_bit_cast(bf16x8, pu), pb_ = __builtin_bit_cast(bf16x8, pv);
; #pragma unroll
;         for (int vt = 0; vt < 2; ++vt) {
;           const char* vp = cur + KBYTES + (vt * 32 + r) * VROW + (t2 * 32 + 16 * s2 + 4 * hh) * 2;
;           const uint2 lo = *(const uint2*)(vp), hi = *(const uint2*)(vp + 16);
;           uint4 vu; vu.x = lo.x; vu.y = lo.y; vu.z = hi.x; vu.w = hi.y;
;           const bf16x8 vf = __builtin_bit_cast(bf16x8, vu);
;           oa[vt] = MFMA(vf, pa_, oa[vt]);
;           ob[vt] = MFMA(vf, pb_, ob[vt]);
;         }
;       }
;       SB_;
;     }
	v_mfma_f32_32x32x16_bf16 v[80:95], v[226:229], v[116:119], v[80:95]
	v_mfma_f32_32x32x16_bf16 v[96:111], v[226:229], v[120:123], v[96:111]
	s_waitcnt vmcnt(0)
	ds_write2_b64 v238, v[160:161], v[162:163] offset1:1
	v_cvt_pk_bf16_f32 v242, v186, v190
	v_cvt_pk_bf16_f32 v243, v192, v180
	v_cvt_pk_bf16_f32 v244, v182, v184
	v_cvt_pk_bf16_f32 v245, v176, v178
	v_cvt_pk_bf16_f32 v246, v187, v191
	v_cvt_pk_bf16_f32 v247, v193, v181
	v_cvt_pk_bf16_f32 v248, v183, v185
	v_cvt_pk_bf16_f32 v249, v177, v179
	s_nop 3
	v_exp_f32_e32 v168, v80
	v_exp_f32_e32 v213, v81
	v_exp_f32_e32 v233, v96
	v_exp_f32_e32 v96, v82
	v_exp_f32_e32 v234, v97
	v_exp_f32_e32 v97, v83
	v_add_f32_e32 v80, 0, v168
	v_exp_f32_e32 v235, v98
	v_exp_f32_e32 v98, v84
	v_mfma_f32_32x32x16_bf16 v[48:63], v[214:217], v[242:245], v[48:63]
	v_add_f32_e32 v80, v213, v80
	v_exp_f32_e32 v236, v99
	v_exp_f32_e32 v99, v85
	v_add_f32_e32 v80, v96, v80
	v_add_f32_e32 v80, v97, v80
	v_add_f32_e32 v80, v98, v80
	v_exp_f32_e32 v237, v100
	v_exp_f32_e32 v241, v101
	v_exp_f32_e32 v100, v86
	v_exp_f32_e32 v101, v102
	v_exp_f32_e32 v102, v87
	v_exp_f32_e32 v103, v103
	v_mfma_f32_32x32x16_bf16 v[16:31], v[222:225], v[242:245], v[16:31]
	v_exp_f32_e32 v218, v88
	v_exp_f32_e32 v219, v104
	v_exp_f32_e32 v104, v89
	v_exp_f32_e32 v105, v105
	v_exp_f32_e32 v226, v90
	v_exp_f32_e32 v227, v106
	v_exp_f32_e32 v106, v91
	v_exp_f32_e32 v107, v107
	v_mfma_f32_32x32x16_bf16 v[32:47], v[214:217], v[246:249], v[32:47]
	v_exp_f32_e32 v228, v92
	v_exp_f32_e32 v229, v108
	v_exp_f32_e32 v108, v93
	v_exp_f32_e32 v109, v109
	v_exp_f32_e32 v230, v94
	v_exp_f32_e32 v231, v110
	v_exp_f32_e32 v110, v95
	v_exp_f32_e32 v111, v111
	v_mfma_f32_32x32x16_bf16 v[0:15], v[222:225], v[246:249], v[0:15]
	v_add_f32_e32 v232, v99, v80
	v_cvt_pk_bf16_f32 v88, v233, v234
	v_cvt_pk_bf16_f32 v89, v235, v236
	v_cvt_pk_bf16_f32 v90, v237, v241
	v_cvt_pk_bf16_f32 v91, v101, v103
	ds_read2_b64 v[80:83], v239 offset0:8 offset1:10
	ds_read2_b64 v[246:249], v240 offset0:40 offset1:42
	v_cvt_pk_bf16_f32 v84, v168, v213
	v_cvt_pk_bf16_f32 v85, v96, v97
	v_cvt_pk_bf16_f32 v86, v98, v99
	v_cvt_pk_bf16_f32 v87, v100, v102
	s_waitcnt lgkmcnt(0)
	s_nop 0
	v_mfma_f32_32x32x16_bf16 v[48:63], v[80:83], v[84:87], v[48:63]
	v_mfma_f32_32x32x16_bf16 v[32:47], v[80:83], v[88:91], v[32:47]
	ds_read2_b64 v[92:95], v239 offset0:12 offset1:14
	ds_read2_b64 v[96:99], v240 offset0:44 offset1:46
	s_waitcnt lgkmcnt(2)
	v_mfma_f32_32x32x16_bf16 v[16:31], v[246:249], v[84:87], v[16:31]
	v_add_f32_e32 v84, 0, v233
	v_add_f32_e32 v84, v234, v84
	v_add_f32_e32 v84, v235, v84
	v_add_f32_e32 v84, v236, v84
	v_add_f32_e32 v84, v237, v84
	v_add_f32_e32 v233, v241, v84
	v_pk_add_f32 v[84:85], v[188:189], v[194:195]
	v_mfma_f32_32x32x16_bf16 v[0:15], v[246:249], v[88:91], v[0:15]
	v_add_f32_e64 v80, v186, v84
	v_add_f32_e64 v81, v187, v85
	v_add_f32_e64 v90, v100, v232
	v_add_f32_e64 v91, v101, v233
	v_add_f32_e64 v80, v190, v80
	v_add_f32_e64 v81, v191, v81
	v_pk_add_f32 v[90:91], v[102:103], v[90:91]
	v_pk_add_f32 v[84:85], v[192:193], v[80:81]
	v_cvt_pk_bf16_f32 v80, v218, v104
	v_pk_add_f32 v[84:85], v[180:181], v[84:85]
	v_cvt_pk_bf16_f32 v81, v226, v106
	v_pk_add_f32 v[84:85], v[182:183], v[84:85]
	v_cvt_pk_bf16_f32 v82, v228, v108
	v_cvt_pk_bf16_f32 v83, v230, v110
	v_pk_add_f32 v[88:89], v[184:185], v[84:85]
	v_cvt_pk_bf16_f32 v84, v219, v105
	v_cvt_pk_bf16_f32 v85, v227, v107
	v_cvt_pk_bf16_f32 v86, v229, v109
	v_cvt_pk_bf16_f32 v87, v231, v111
	v_pk_add_f32 v[90:91], v[218:219], v[90:91]
	s_waitcnt lgkmcnt(1)
	v_mfma_f32_32x32x16_bf16 v[48:63], v[92:95], v[80:83], v[48:63]
	v_add_f32_e64 v90, v104, v90
	v_add_f32_e64 v91, v105, v91
	v_add_f32_e64 v88, v176, v88
	v_add_f32_e64 v89, v177, v89
	v_add_f32_e64 v88, v178, v88
	v_add_f32_e64 v89, v179, v89
	v_pk_add_f32 v[88:89], v[166:167], v[88:89]
	v_mfma_f32_32x32x16_bf16 v[32:47], v[92:95], v[84:87], v[32:47]
	s_waitcnt lgkmcnt(0)
	v_mfma_f32_32x32x16_bf16 v[16:31], v[96:99], v[80:83], v[16:31]
	v_add_f32_e64 v80, v226, v90
	v_add_f32_e64 v81, v227, v91
	v_add_f32_e64 v80, v106, v80
	v_add_f32_e64 v81, v107, v81
	v_add_f32_e64 v80, v228, v80
	v_add_f32_e64 v81, v229, v81
	v_pk_add_f32 v[80:81], v[108:109], v[80:81]
	v_mfma_f32_32x32x16_bf16 v[0:15], v[96:99], v[84:87], v[0:15]
	v_add_f32_e64 v80, v230, v80
	v_add_f32_e64 v81, v231, v81
	v_add_f32_e64 v80, v110, v80
	v_add_f32_e64 v81, v111, v81
	v_add_f32_e64 v166, v88, v80
	v_add_f32_e64 v167, v89, v81
	s_add_i32 s8, s8, 1
	v_lshl_add_u64 v[170:171], v[170:171], 0, s[30:31]
	v_lshl_add_u64 v[172:173], v[172:173], 0, s[34:35]
	s_cmp_lg_u32 s8, 36
	v_lshl_add_u64 v[174:175], v[174:175], 0, s[34:35]
	s_waitcnt lgkmcnt(0)
	s_barrier
	s_cbranch_scc0 .LBB0_551
